# wi 11/21 with RG-LRU gate weight conversion deferred to the end of the item setup (all setup loads in one round trip)
# baseline (speedup 1.0000x reference)
.LBB0_485:
	s_and_b64 vcc, exec, s[4:5]
	s_cbranch_vccz .LBB0_476
	v_mov_b32_e32 v2, s82
	ds_read_b64 v[4:5], v2
	s_lshl_b32 s4, s91, 5
	s_lshr_b32 s7, s91, 1
	s_and_b32 s6, s4, 32
	s_lshl_b32 s4, s68, 3
	s_or_b32 s4, s4, s7
	s_ashr_i32 s5, s4, 31
	s_lshl_b32 s8, s7, 6
	s_lshl_b64 s[4:5], s[4:5], 18
	s_waitcnt lgkmcnt(0)
	v_readfirstlane_b32 s9, v4
	s_lshl_b32 s12, s6, 2
	v_readfirstlane_b32 s11, v5
	s_add_u32 s10, s9, s12
	v_bfe_u32 v121, v114, 4, 2
	v_mov_b32_e32 v2, s83
	s_addc_u32 s11, s11, 0
	v_mov_b32_e32 v61, v3
	s_lshl_b32 s9, s7, 14
	ds_read_b64 v[22:23], v2
	v_lshl_add_u64 v[4:5], s[10:11], 0, v[60:61]
	v_lshl_or_b32 v2, v121, 11, s9
	v_lshl_add_u64 v[18:19], v[4:5], 0, v[2:3]
	v_mov_b32_e32 v27, v3
	v_or_b32_e32 v26, 0x2000, v2
	v_lshl_add_u64 v[4:5], v[4:5], 0, v[26:27]
	s_waitcnt lgkmcnt(0)
	v_readfirstlane_b32 s9, v22
	v_readfirstlane_b32 s11, v23
	s_add_u32 s10, s9, s12
	s_addc_u32 s11, s11, 0
	s_or_b32 s8, s8, s6
	v_mov_b32_e32 v38, s85
	v_mov_b32_e32 v39, s86
	s_lshl_b32 s7, s7, 8
	v_and_b32_e32 v123, 7, v114
	v_mov_b32_e32 v80, v3
	v_mov_b32_e32 v81, v3
	v_mov_b32_e32 v78, v3
	v_mov_b32_e32 v79, v3
	v_mov_b64_e32 v[84:85], v[80:81]
	v_and_b32_e32 v178, -8, v114
	v_mov_b64_e32 v[82:83], v[78:79]
	v_lshl_add_u64 v[46:47], s[10:11], 0, v[60:61]
	v_lshl_add_u64 v[34:35], v[46:47], 0, v[2:3]
	v_lshl_add_u64 v[46:47], v[46:47], 0, v[26:27]
	global_load_dword v6, v[18:19], off
	global_load_dword v198, v[18:19], off offset:256
	global_load_dword v7, v[18:19], off offset:512
	global_load_dword v199, v[18:19], off offset:768
	global_load_dword v8, v[18:19], off offset:1024
	global_load_dword v200, v[18:19], off offset:1280
	global_load_dword v9, v[18:19], off offset:1536
	global_load_dword v201, v[18:19], off offset:1792
	global_load_dword v10, v[4:5], off
	global_load_dword v202, v[4:5], off offset:256
	global_load_dword v11, v[4:5], off offset:512
	global_load_dword v203, v[4:5], off offset:768
	global_load_dword v12, v[4:5], off offset:1024
	global_load_dword v204, v[4:5], off offset:1280
	global_load_dword v13, v[4:5], off offset:1536
	global_load_dword v205, v[4:5], off offset:1792
	global_load_dword v14, v[18:19], off offset:64
	global_load_dword v206, v[18:19], off offset:320
	global_load_dword v15, v[18:19], off offset:576
	global_load_dword v207, v[18:19], off offset:832
	global_load_dword v16, v[18:19], off offset:1088
	global_load_dword v208, v[18:19], off offset:1344
	global_load_dword v17, v[18:19], off offset:1600
	global_load_dword v209, v[18:19], off offset:1856
	global_load_dword v18, v[4:5], off offset:64
	global_load_dword v210, v[4:5], off offset:320
	global_load_dword v19, v[4:5], off offset:576
	global_load_dword v211, v[4:5], off offset:832
	global_load_dword v20, v[4:5], off offset:1088
	global_load_dword v212, v[4:5], off offset:1344
	global_load_dword v21, v[4:5], off offset:1600
	global_load_dword v213, v[4:5], off offset:1856
	global_load_dword v22, v[34:35], off
	global_load_dword v214, v[34:35], off offset:256
	global_load_dword v23, v[34:35], off offset:512
	global_load_dword v215, v[34:35], off offset:768
	global_load_dword v24, v[34:35], off offset:1024
	global_load_dword v216, v[34:35], off offset:1280
	global_load_dword v25, v[34:35], off offset:1536
	global_load_dword v217, v[34:35], off offset:1792
	global_load_dword v26, v[46:47], off
	global_load_dword v218, v[46:47], off offset:256
	global_load_dword v27, v[46:47], off offset:512
	global_load_dword v219, v[46:47], off offset:768
	global_load_dword v28, v[46:47], off offset:1024
	global_load_dword v220, v[46:47], off offset:1280
	global_load_dword v29, v[46:47], off offset:1536
	global_load_dword v221, v[46:47], off offset:1792
	global_load_dword v30, v[34:35], off offset:64
	global_load_dword v222, v[34:35], off offset:320
	global_load_dword v31, v[34:35], off offset:576
	global_load_dword v223, v[34:35], off offset:832
	global_load_dword v32, v[34:35], off offset:1088
	global_load_dword v224, v[34:35], off offset:1344
	global_load_dword v33, v[34:35], off offset:1600
	global_load_dword v225, v[34:35], off offset:1856
	global_load_dword v34, v[46:47], off offset:64
	global_load_dword v226, v[46:47], off offset:320
	global_load_dword v35, v[46:47], off offset:576
	global_load_dword v227, v[46:47], off offset:832
	global_load_dword v36, v[46:47], off offset:1088
	global_load_dword v228, v[46:47], off offset:1344
	global_load_dword v37, v[46:47], off offset:1600
	global_load_dword v229, v[46:47], off offset:1856
	v_or_b32_e32 v2, s8, v115
	v_lshlrev_b32_e32 v44, 2, v2
	v_mov_b32_e32 v5, s84
	v_or_b32_e32 v40, 64, v44
	v_lshlrev_b32_e32 v2, 5, v123
	ds_read_b64 v[4:5], v5
	ds_read_b64 v[42:43], v38
	global_load_dword v124, v40, s[2:3]
	ds_read2_b64 v[38:41], v39 offset1:1
	s_waitcnt lgkmcnt(2)
	v_readfirstlane_b32 s8, v4
	v_readfirstlane_b32 s9, v5
	s_waitcnt lgkmcnt(1)
	v_readfirstlane_b32 s10, v42
	s_waitcnt lgkmcnt(0)
	v_readfirstlane_b32 s12, v38
	v_readfirstlane_b32 s11, v43
	v_readfirstlane_b32 s13, v39
	global_load_dword v118, v44, s[8:9]
	s_nop 2
	global_load_dword v122, v44, s[10:11]
	global_load_dword v125, v44, s[10:11] offset:64
	global_load_dword v126, v44, s[8:9] offset:64
	global_load_dword v127, v44, s[2:3]
	s_add_u32 s8, s12, s7
	s_addc_u32 s9, s13, 0
	v_lshl_add_u64 v[4:5], s[8:9], 0, v[2:3]
	v_readfirstlane_b32 s14, v40
	v_add_co_u32_e32 v62, vcc, s87, v4
	v_readfirstlane_b32 s15, v41
	s_add_u32 s10, s14, s7
	v_lshl_add_u64 v[58:59], v[4:5], 0, s[64:65]
	v_addc_co_u32_e32 v63, vcc, 0, v5, vcc
	global_load_dwordx4 v[38:41], v2, s[8:9] offset:16
	global_load_dwordx4 v[42:45], v2, s[8:9]
	global_load_dwordx4 v[46:49], v2, s[8:9] offset:2064
	global_load_dwordx4 v[50:53], v2, s[8:9] offset:2048
	s_addc_u32 s11, s15, 0
	v_lshl_add_u64 v[4:5], v[4:5], 0, s[66:67]
	global_load_dwordx4 v[54:57], v[62:63], off
	s_nop 0
	global_load_dwordx4 v[58:61], v[58:59], off offset:16
	s_nop 0
	global_load_dwordx4 v[62:65], v[62:63], off offset:2048
	s_nop 0
	global_load_dwordx4 v[66:69], v[4:5], off offset:16
	global_load_dwordx4 v[70:73], v2, s[10:11] offset:16
	global_load_dwordx4 v[74:77], v2, s[10:11]
	s_add_u32 s4, s72, s4
	s_addc_u32 s5, s73, s5
	v_lshlrev_b32_e32 v2, 4, v123
	v_lshl_add_u64 v[180:181], s[4:5], 0, v[2:3]
	v_cmp_lt_i32_e32 vcc, 7, v114
	s_and_saveexec_b64 s[4:5], vcc
	s_cbranch_execz .LBB0_488
	v_add_u32_e32 v2, -3, v178
	v_lshlrev_b64 v[4:5], 7, v[2:3]
	v_lshl_add_u64 v[4:5], v[180:181], 0, v[4:5]
	global_load_dwordx4 v[82:85], v[4:5], off nt

.LBB0_508:
	s_or_b64 exec, exec, s[4:5]
	s_andn2_b32 s90, s90, 63
	v_lshl_or_b32 v140, v121, 2, s90
	v_or_b32_e32 v5, s90, v115
	v_or_b32_e32 v141, s6, v115
	v_and_b32_e32 v2, 0x70, v119
	v_and_b32_e32 v115, 4, v120
	v_mul_lo_u32 v179, v140, s80
	v_mul_lo_u32 v145, v140, s88
	v_or_b32_e32 v146, 16, v140
	v_or_b32_e32 v148, 32, v140
	v_or_b32_e32 v140, 48, v140
	s_waitcnt vmcnt(14)
	v_mul_f32_e32 v114, 0xbfb8aa3b, v118
	s_waitcnt vmcnt(13)
	v_mul_f32_e32 v118, 0xbfb8aa3b, v122
	s_waitcnt vmcnt(10)
	v_mul_f32_e32 v4, 0x3fb8aa3b, v127
	v_mul_f32_e32 v122, 0xbfb8aa3b, v126
	v_mul_f32_e32 v126, 0xbfb8aa3b, v125
	v_mul_f32_e32 v182, 0x3fb8aa3b, v124
	v_lshl_add_u32 v138, v123, 4, 0
	v_lshl_add_u32 v139, v121, 4, 0
	v_add3_u32 v2, 0, v2, v115
	v_mul_lo_u32 v142, v178, s88
	v_mul_lo_u32 v143, v116, s88
	v_mul_lo_u32 v144, v5, s88
	v_lshl_add_u32 v141, v141, 1, 0
	v_mul_lo_u32 v146, v146, s88
	v_add_u32_e32 v147, 0x1210, v179
	v_mul_lo_u32 v148, v148, s88
	v_mul_lo_u32 v140, v140, s88
	v_mov_b32_e32 v115, v114
	v_mov_b32_e32 v116, v114
	v_mov_b32_e32 v117, v114
	v_mov_b32_e32 v123, v122
	v_mov_b32_e32 v124, v122
	v_mov_b32_e32 v125, v122
	v_mov_b32_e32 v119, v118
	v_mov_b32_e32 v120, v118
	v_mov_b32_e32 v121, v118
	v_mov_b32_e32 v127, v126
	v_mov_b32_e32 v128, v126
	v_mov_b32_e32 v129, v126
	v_mov_b32_e32 v5, v4
	v_mov_b32_e32 v184, v4
	v_mov_b32_e32 v185, v4
	v_mov_b32_e32 v183, v182
	v_mov_b32_e32 v186, v182
	v_mov_b32_e32 v187, v182
	s_mov_b32 s6, 0
	v_add_u32_e32 v190, v138, v142
	v_add_u32_e32 v191, v138, v143
	v_add_u32_e32 v192, v139, v144
	v_add_u32_e32 v193, v141, v145
	v_add_u32_e32 v194, v141, v146
	v_add_u32_e32 v195, v2, v147
	v_add_u32_e32 v196, v141, v148
	v_add_u32_e32 v197, v141, v140
	s_mov_b32 s7, 0
	s_waitcnt vmcnt(0)
	v_mul_f32_e32 v6, 0xbfb8aa3b, v6
	v_mul_f32_e32 v198, 0xbfb8aa3b, v198
	v_cvt_pk_bf16_f32 v6, v6, v198
	v_mul_f32_e32 v7, 0xbfb8aa3b, v7
	v_mul_f32_e32 v199, 0xbfb8aa3b, v199
	v_cvt_pk_bf16_f32 v7, v7, v199
	v_mul_f32_e32 v8, 0xbfb8aa3b, v8
	v_mul_f32_e32 v200, 0xbfb8aa3b, v200
	v_cvt_pk_bf16_f32 v8, v8, v200
	v_mul_f32_e32 v9, 0xbfb8aa3b, v9
	v_mul_f32_e32 v201, 0xbfb8aa3b, v201
	v_cvt_pk_bf16_f32 v9, v9, v201
	v_mul_f32_e32 v10, 0xbfb8aa3b, v10
	v_mul_f32_e32 v202, 0xbfb8aa3b, v202
	v_cvt_pk_bf16_f32 v10, v10, v202
	v_mul_f32_e32 v11, 0xbfb8aa3b, v11
	v_mul_f32_e32 v203, 0xbfb8aa3b, v203
	v_cvt_pk_bf16_f32 v11, v11, v203
	v_mul_f32_e32 v12, 0xbfb8aa3b, v12
	v_mul_f32_e32 v204, 0xbfb8aa3b, v204
	v_cvt_pk_bf16_f32 v12, v12, v204
	v_mul_f32_e32 v13, 0xbfb8aa3b, v13
	v_mul_f32_e32 v205, 0xbfb8aa3b, v205
	v_cvt_pk_bf16_f32 v13, v13, v205
	v_mul_f32_e32 v14, 0xbfb8aa3b, v14
	v_mul_f32_e32 v206, 0xbfb8aa3b, v206
	v_cvt_pk_bf16_f32 v14, v14, v206
	v_mul_f32_e32 v15, 0xbfb8aa3b, v15
	v_mul_f32_e32 v207, 0xbfb8aa3b, v207
	v_cvt_pk_bf16_f32 v15, v15, v207
	v_mul_f32_e32 v16, 0xbfb8aa3b, v16
	v_mul_f32_e32 v208, 0xbfb8aa3b, v208
	v_cvt_pk_bf16_f32 v16, v16, v208
	v_mul_f32_e32 v17, 0xbfb8aa3b, v17
	v_mul_f32_e32 v209, 0xbfb8aa3b, v209
	v_cvt_pk_bf16_f32 v17, v17, v209
	v_mul_f32_e32 v18, 0xbfb8aa3b, v18
	v_mul_f32_e32 v210, 0xbfb8aa3b, v210
	v_cvt_pk_bf16_f32 v18, v18, v210
	v_mul_f32_e32 v19, 0xbfb8aa3b, v19
	v_mul_f32_e32 v211, 0xbfb8aa3b, v211
	v_cvt_pk_bf16_f32 v19, v19, v211
	v_mul_f32_e32 v20, 0xbfb8aa3b, v20
	v_mul_f32_e32 v212, 0xbfb8aa3b, v212
	v_cvt_pk_bf16_f32 v20, v20, v212
	v_mul_f32_e32 v21, 0xbfb8aa3b, v21
	v_mul_f32_e32 v213, 0xbfb8aa3b, v213
	v_cvt_pk_bf16_f32 v21, v21, v213
	v_mul_f32_e32 v22, 0xbfb8aa3b, v22
	v_mul_f32_e32 v214, 0xbfb8aa3b, v214
	v_cvt_pk_bf16_f32 v22, v22, v214
	v_mul_f32_e32 v23, 0xbfb8aa3b, v23
	v_mul_f32_e32 v215, 0xbfb8aa3b, v215
	v_cvt_pk_bf16_f32 v23, v23, v215
	v_mul_f32_e32 v24, 0xbfb8aa3b, v24
	v_mul_f32_e32 v216, 0xbfb8aa3b, v216
	v_cvt_pk_bf16_f32 v24, v24, v216
	v_mul_f32_e32 v25, 0xbfb8aa3b, v25
	v_mul_f32_e32 v217, 0xbfb8aa3b, v217
	v_cvt_pk_bf16_f32 v25, v25, v217
	v_mul_f32_e32 v26, 0xbfb8aa3b, v26
	v_mul_f32_e32 v218, 0xbfb8aa3b, v218
	v_cvt_pk_bf16_f32 v26, v26, v218
	v_mul_f32_e32 v27, 0xbfb8aa3b, v27
	v_mul_f32_e32 v219, 0xbfb8aa3b, v219
	v_cvt_pk_bf16_f32 v27, v27, v219
	v_mul_f32_e32 v28, 0xbfb8aa3b, v28
	v_mul_f32_e32 v220, 0xbfb8aa3b, v220
	v_cvt_pk_bf16_f32 v28, v28, v220
	v_mul_f32_e32 v29, 0xbfb8aa3b, v29
	v_mul_f32_e32 v221, 0xbfb8aa3b, v221
	v_cvt_pk_bf16_f32 v29, v29, v221
	v_mul_f32_e32 v30, 0xbfb8aa3b, v30
	v_mul_f32_e32 v222, 0xbfb8aa3b, v222
	v_cvt_pk_bf16_f32 v30, v30, v222
	v_mul_f32_e32 v31, 0xbfb8aa3b, v31
	v_mul_f32_e32 v223, 0xbfb8aa3b, v223
	v_cvt_pk_bf16_f32 v31, v31, v223
	v_mul_f32_e32 v32, 0xbfb8aa3b, v32
	v_mul_f32_e32 v224, 0xbfb8aa3b, v224
	v_cvt_pk_bf16_f32 v32, v32, v224
	v_mul_f32_e32 v33, 0xbfb8aa3b, v33
	v_mul_f32_e32 v225, 0xbfb8aa3b, v225
	v_cvt_pk_bf16_f32 v33, v33, v225
	v_mul_f32_e32 v34, 0xbfb8aa3b, v34
	v_mul_f32_e32 v226, 0xbfb8aa3b, v226
	v_cvt_pk_bf16_f32 v34, v34, v226
	v_mul_f32_e32 v35, 0xbfb8aa3b, v35
	v_mul_f32_e32 v227, 0xbfb8aa3b, v227
	v_cvt_pk_bf16_f32 v35, v35, v227
	v_mul_f32_e32 v36, 0xbfb8aa3b, v36
	v_mul_f32_e32 v228, 0xbfb8aa3b, v228
	v_cvt_pk_bf16_f32 v36, v36, v228
	v_mul_f32_e32 v37, 0xbfb8aa3b, v37
	v_mul_f32_e32 v229, 0xbfb8aa3b, v229
	v_cvt_pk_bf16_f32 v37, v37, v229
	s_branch .LBB0_510
